# p3a S1: the l2-norm 16-lane reductions use four DPP adds (quad_perm, row_half_mirror, row_mirror) instead of four ds_bpermute round trips per token
# speedup vs baseline: 1.0146x; 1.0146x over previous
.Lp3a_s2h_skip:
	v_pk_fma_f32 v[52:53], v[110:111], v[48:49], v[52:53]
	v_add_f32_e32 v27, 1.0, v27
	v_mul_f32_e32 v54, 0xbfb8aa3b, v52
	v_mul_f32_e32 v55, 0xbfb8aa3b, v53
	v_rcp_f32_e32 v26, v26
	v_rcp_f32_e32 v27, v27
	v_exp_f32_e32 v54, v54
	v_exp_f32_e32 v55, v55
	v_lshlrev_b32_e32 v28, 16, v121
	v_pk_mul_f32 v[22:23], v[22:23], v[26:27]
	v_add_f32_e32 v26, 1.0, v54
	v_add_f32_e32 v27, 1.0, v55
	v_lshlrev_b32_e32 v54, 16, v117
	v_and_b32_e32 v55, 0xffff0000, v117
	v_and_b32_e32 v29, 0xffff0000, v121
	v_pk_fma_f32 v[54:55], v[4:5], v[54:55], 0 op_sel_hi:[1,1,0]
	v_lshlrev_b32_e32 v36, 16, v125
	v_and_b32_e32 v37, 0xffff0000, v125
	v_pk_fma_f32 v[54:55], v[16:17], v[28:29], v[54:55]
	v_lshlrev_b32_e32 v44, 16, v129
	v_and_b32_e32 v45, 0xffff0000, v129
	v_pk_fma_f32 v[54:55], v[104:105], v[36:37], v[54:55]
	v_rcp_f32_e32 v26, v26
	v_pk_fma_f32 v[54:55], v[112:113], v[44:45], v[54:55]
	v_rcp_f32_e32 v27, v27
	v_mul_f32_e32 v56, 0xbfb8aa3b, v54
	v_mul_f32_e32 v57, 0xbfb8aa3b, v55
	v_exp_f32_e32 v56, v56
	v_exp_f32_e32 v57, v57
	v_pk_mul_f32 v[24:25], v[20:21], v[20:21]
	v_pk_mul_f32 v[58:59], v[22:23], v[22:23]
	v_add_f32_e32 v56, 1.0, v56
	v_add_f32_e32 v57, 1.0, v57
	v_rcp_f32_e32 v56, v56
	v_rcp_f32_e32 v57, v57
	v_add_f32_e32 v24, v24, v25
	v_pk_mul_f32 v[52:53], v[52:53], v[26:27]
	v_add_f32_e32 v24, v58, v24
	v_and_b32_e32 v167, 64, v184
	v_pk_mul_f32 v[26:27], v[52:53], v[52:53]
	v_add_f32_e32 v24, v59, v24
	v_xor_b32_e32 v19, 1, v184
	v_add_u32_e32 v60, 64, v167
	v_pk_mul_f32 v[54:55], v[54:55], v[56:57]
	v_add_f32_e32 v24, v26, v24
	v_cmp_lt_i32_e32 vcc, v19, v60
	v_pk_mul_f32 v[56:57], v[54:55], v[54:55]
	v_add_f32_e32 v24, v27, v24
	v_cndmask_b32_e32 v19, v184, v19, vcc
	v_add_f32_e32 v24, v56, v24
	v_lshlrev_b32_e32 v19, 2, v19
	v_add_f32_e32 v24, v57, v24
	v_xor_b32_e32 v26, 2, v184
	v_cmp_lt_i32_e32 vcc, v26, v60
	v_mov_b32_e32 v160, v1
	s_nop 1
	v_add_f32_dpp v24, v24, v24 quad_perm:[1,0,3,2] row_mask:0xf bank_mask:0xf
	v_cndmask_b32_e32 v26, v184, v26, vcc
	v_lshlrev_b32_e32 v168, 2, v26
	v_xor_b32_e32 v26, 4, v184
	v_cmp_lt_i32_e32 vcc, v26, v60
	v_cmp_gt_i32_e64 s[6:7], 16, v160
	v_mov_b32_e32 v56, 1.0
	v_cndmask_b32_e32 v26, v184, v26, vcc
	v_lshlrev_b32_e32 v173, 2, v26
	s_nop 1
	v_add_f32_dpp v24, v24, v24 quad_perm:[2,3,0,1] row_mask:0xf bank_mask:0xf
	v_xor_b32_e32 v26, 8, v184
	v_cmp_lt_i32_e32 vcc, v26, v60
	v_cndmask_b32_e64 v161, 1.0, v187, s[6:7]
	v_cmp_gt_i32_e64 s[4:5], 32, v160
	v_cndmask_b32_e32 v26, v184, v26, vcc
	v_lshlrev_b32_e32 v175, 2, v26
	s_nop 1
	v_add_f32_dpp v24, v24, v24 row_half_mirror row_mask:0xf bank_mask:0xf
	s_nop 1
	v_add_f32_dpp v24, v24, v24 row_mirror row_mask:0xf bank_mask:0xf
	s_and_saveexec_b64 s[8:9], s[4:5]
	s_cbranch_execz .LBB0_502
	v_add_f32_e32 v24, 0x358637bd, v24
	v_mul_f32_e32 v25, 0x4b800000, v24
	v_cmp_gt_f32_e32 vcc, s48, v24
	s_nop 1
	v_cndmask_b32_e32 v24, v24, v25, vcc
	v_rsq_f32_e32 v24, v24
	s_nop 0
	v_mul_f32_e32 v25, 0x45800000, v24
	v_cndmask_b32_e32 v24, v24, v25, vcc
	v_mul_f32_e32 v56, v161, v24

.LBB0_504:
	s_or_b64 exec, exec, s[8:9]
	v_pk_fma_f32 v[34:35], v[6:7], v[34:35], 0 op_sel_hi:[1,1,0]
	v_lshlrev_b32_e32 v60, 16, v130
	v_pk_fma_f32 v[34:35], v[10:11], v[42:43], v[34:35]
	v_and_b32_e32 v61, 0xffff0000, v130
	v_pk_fma_f32 v[34:35], v[98:99], v[50:51], v[34:35]
	v_pk_fma_f32 v[32:33], v[8:9], v[32:33], 0 op_sel_hi:[1,1,0]
	v_pk_fma_f32 v[34:35], v[106:107], v[60:61], v[34:35]
	v_pk_fma_f32 v[32:33], v[12:13], v[40:41], v[32:33]
	v_mul_f32_e32 v52, 0xbfb8aa3b, v34
	v_mul_f32_e32 v53, 0xbfb8aa3b, v35
	v_exp_f32_e32 v52, v52
	v_exp_f32_e32 v53, v53
	v_lshlrev_b32_e32 v58, 16, v131
	v_and_b32_e32 v59, 0xffff0000, v131
	v_add_f32_e32 v52, 1.0, v52
	v_add_f32_e32 v53, 1.0, v53
	v_rcp_f32_e32 v52, v52
	v_rcp_f32_e32 v53, v53
	v_pk_fma_f32 v[32:33], v[100:101], v[46:47], v[32:33]
	v_pk_fma_f32 v[30:31], v[2:3], v[30:31], 0 op_sel_hi:[1,1,0]
	v_pk_fma_f32 v[32:33], v[108:109], v[58:59], v[32:33]
	v_pk_mul_f32 v[34:35], v[34:35], v[52:53]
	v_mul_f32_e32 v52, 0xbfb8aa3b, v32
	v_mul_f32_e32 v53, 0xbfb8aa3b, v33
	v_exp_f32_e32 v52, v52
	v_exp_f32_e32 v53, v53
	v_pk_fma_f32 v[30:31], v[14:15], v[38:39], v[30:31]
	v_lshlrev_b32_e32 v62, 16, v132
	v_add_f32_e32 v52, 1.0, v52
	v_add_f32_e32 v53, 1.0, v53
	v_and_b32_e32 v63, 0xffff0000, v132
	v_rcp_f32_e32 v52, v52
	v_rcp_f32_e32 v53, v53
	v_pk_fma_f32 v[30:31], v[102:103], v[48:49], v[30:31]
	v_pk_fma_f32 v[28:29], v[4:5], v[28:29], 0 op_sel_hi:[1,1,0]
	v_pk_fma_f32 v[64:65], v[110:111], v[62:63], v[30:31]
	v_pk_fma_f32 v[28:29], v[16:17], v[36:37], v[28:29]
	v_mul_f32_e32 v30, 0xbfb8aa3b, v64
	v_lshlrev_b32_e32 v56, 16, v133
	v_and_b32_e32 v57, 0xffff0000, v133
	v_exp_f32_e32 v66, v30
	v_mul_f32_e32 v30, 0xbfb8aa3b, v65
	v_pk_fma_f32 v[28:29], v[104:105], v[44:45], v[28:29]
	v_exp_f32_e32 v67, v30
	v_pk_mul_f32 v[30:31], v[32:33], v[52:53]
	v_pk_fma_f32 v[52:53], v[112:113], v[56:57], v[28:29]
	v_add_f32_e32 v32, 1.0, v66
	v_mul_f32_e32 v28, 0xbfb8aa3b, v52
	v_exp_f32_e32 v28, v28
	v_mul_f32_e32 v29, 0xbfb8aa3b, v53
	v_exp_f32_e32 v29, v29
	v_add_f32_e32 v33, 1.0, v67
	v_rcp_f32_e32 v32, v32
	v_rcp_f32_e32 v33, v33
	v_add_f32_e32 v28, 1.0, v28
	v_rcp_f32_e32 v66, v28
	v_add_f32_e32 v28, 1.0, v29
	v_pk_mul_f32 v[54:55], v[34:35], v[34:35]
	v_rcp_f32_e32 v67, v28
	v_pk_mul_f32 v[68:69], v[30:31], v[30:31]
	v_add_f32_e32 v54, v54, v55
	v_pk_mul_f32 v[28:29], v[64:65], v[32:33]
	v_add_f32_e32 v54, v68, v54
	v_pk_mul_f32 v[32:33], v[28:29], v[28:29]
	v_add_f32_e32 v54, v69, v54
	v_pk_mul_f32 v[52:53], v[52:53], v[66:67]
	v_add_f32_e32 v32, v32, v54
	v_pk_mul_f32 v[64:65], v[52:53], v[52:53]
	v_add_f32_e32 v32, v33, v32
	v_add_f32_e32 v32, v64, v32
	v_add_f32_e32 v32, v65, v32
	v_mov_b32_e32 v54, 1.0
	s_nop 1
	v_add_f32_dpp v32, v32, v32 quad_perm:[1,0,3,2] row_mask:0xf bank_mask:0xf
	s_nop 1
	v_add_f32_dpp v32, v32, v32 quad_perm:[2,3,0,1] row_mask:0xf bank_mask:0xf
	s_nop 1
	v_add_f32_dpp v32, v32, v32 row_half_mirror row_mask:0xf bank_mask:0xf
	s_nop 1
	v_add_f32_dpp v32, v32, v32 row_mirror row_mask:0xf bank_mask:0xf
	s_and_saveexec_b64 s[8:9], s[4:5]
	s_cbranch_execz .LBB0_506
	v_add_f32_e32 v32, 0x358637bd, v32
	v_mul_f32_e32 v33, 0x4b800000, v32
	v_cmp_gt_f32_e32 vcc, s48, v32
	s_nop 1
	v_cndmask_b32_e32 v32, v32, v33, vcc
	v_rsq_f32_e32 v32, v32
	s_nop 0
	v_mul_f32_e32 v33, 0x45800000, v32
	v_cndmask_b32_e32 v32, v32, v33, vcc
	v_mul_f32_e32 v54, v161, v32

.LBB0_508:
	s_or_b64 exec, exec, s[8:9]
	v_pk_fma_f32 v[42:43], v[6:7], v[42:43], 0 op_sel_hi:[1,1,0]
	v_lshlrev_b32_e32 v80, 16, v134
	v_pk_fma_f32 v[42:43], v[10:11], v[50:51], v[42:43]
	v_and_b32_e32 v81, 0xffff0000, v134
	v_pk_fma_f32 v[42:43], v[98:99], v[60:61], v[42:43]
	v_pk_fma_f32 v[40:41], v[8:9], v[40:41], 0 op_sel_hi:[1,1,0]
	v_pk_fma_f32 v[42:43], v[106:107], v[80:81], v[42:43]
	v_pk_fma_f32 v[40:41], v[12:13], v[46:47], v[40:41]
	v_mul_f32_e32 v52, 0xbfb8aa3b, v42
	v_mul_f32_e32 v53, 0xbfb8aa3b, v43
	v_exp_f32_e32 v52, v52
	v_exp_f32_e32 v53, v53
	v_lshlrev_b32_e32 v66, 16, v135
	v_and_b32_e32 v67, 0xffff0000, v135
	v_add_f32_e32 v52, 1.0, v52
	v_add_f32_e32 v53, 1.0, v53
	v_rcp_f32_e32 v52, v52
	v_rcp_f32_e32 v53, v53
	v_pk_fma_f32 v[40:41], v[100:101], v[58:59], v[40:41]
	v_pk_fma_f32 v[38:39], v[2:3], v[38:39], 0 op_sel_hi:[1,1,0]
	v_pk_fma_f32 v[40:41], v[108:109], v[66:67], v[40:41]
	v_pk_mul_f32 v[42:43], v[42:43], v[52:53]
	v_mul_f32_e32 v52, 0xbfb8aa3b, v40
	v_mul_f32_e32 v53, 0xbfb8aa3b, v41
	v_exp_f32_e32 v52, v52
	v_exp_f32_e32 v53, v53
	v_pk_fma_f32 v[38:39], v[14:15], v[48:49], v[38:39]
	v_lshlrev_b32_e32 v72, 16, v136
	v_add_f32_e32 v52, 1.0, v52
	v_add_f32_e32 v53, 1.0, v53
	v_and_b32_e32 v73, 0xffff0000, v136
	v_rcp_f32_e32 v52, v52
	v_rcp_f32_e32 v53, v53
	v_pk_fma_f32 v[38:39], v[102:103], v[62:63], v[38:39]
	v_pk_fma_f32 v[36:37], v[4:5], v[36:37], 0 op_sel_hi:[1,1,0]
	v_pk_fma_f32 v[68:69], v[110:111], v[72:73], v[38:39]
	v_pk_fma_f32 v[36:37], v[16:17], v[44:45], v[36:37]
	v_mul_f32_e32 v38, 0xbfb8aa3b, v68
	v_lshlrev_b32_e32 v54, 16, v137
	v_and_b32_e32 v55, 0xffff0000, v137
	v_exp_f32_e32 v70, v38
	v_mul_f32_e32 v38, 0xbfb8aa3b, v69
	v_pk_fma_f32 v[36:37], v[104:105], v[56:57], v[36:37]
	v_exp_f32_e32 v71, v38
	v_pk_mul_f32 v[38:39], v[40:41], v[52:53]
	v_pk_fma_f32 v[52:53], v[112:113], v[54:55], v[36:37]
	v_add_f32_e32 v40, 1.0, v70
	v_mul_f32_e32 v36, 0xbfb8aa3b, v52
	v_exp_f32_e32 v36, v36
	v_mul_f32_e32 v37, 0xbfb8aa3b, v53
	v_exp_f32_e32 v37, v37
	v_add_f32_e32 v41, 1.0, v71
	v_rcp_f32_e32 v40, v40
	v_rcp_f32_e32 v41, v41
	v_add_f32_e32 v36, 1.0, v36
	v_rcp_f32_e32 v70, v36
	v_add_f32_e32 v36, 1.0, v37
	v_pk_mul_f32 v[64:65], v[42:43], v[42:43]
	v_rcp_f32_e32 v71, v36
	v_pk_mul_f32 v[74:75], v[38:39], v[38:39]
	v_add_f32_e32 v64, v64, v65
	v_pk_mul_f32 v[36:37], v[68:69], v[40:41]
	v_add_f32_e32 v64, v74, v64
	v_pk_mul_f32 v[40:41], v[36:37], v[36:37]
	v_add_f32_e32 v64, v75, v64
	v_pk_mul_f32 v[52:53], v[52:53], v[70:71]
	v_add_f32_e32 v40, v40, v64
	v_pk_mul_f32 v[68:69], v[52:53], v[52:53]
	v_add_f32_e32 v40, v41, v40
	v_add_f32_e32 v40, v68, v40
	v_add_f32_e32 v40, v69, v40
	v_mov_b32_e32 v64, 1.0
	s_nop 1
	v_add_f32_dpp v40, v40, v40 quad_perm:[1,0,3,2] row_mask:0xf bank_mask:0xf
	s_nop 1
	v_add_f32_dpp v40, v40, v40 quad_perm:[2,3,0,1] row_mask:0xf bank_mask:0xf
	s_nop 1
	v_add_f32_dpp v40, v40, v40 row_half_mirror row_mask:0xf bank_mask:0xf
	s_nop 1
	v_add_f32_dpp v40, v40, v40 row_mirror row_mask:0xf bank_mask:0xf
	s_and_saveexec_b64 s[8:9], s[4:5]
	s_cbranch_execz .LBB0_510
	v_add_f32_e32 v40, 0x358637bd, v40
	v_mul_f32_e32 v41, 0x4b800000, v40
	v_cmp_gt_f32_e32 vcc, s48, v40
	s_nop 1
	v_cndmask_b32_e32 v40, v40, v41, vcc
	v_rsq_f32_e32 v40, v40
	s_nop 0
	v_mul_f32_e32 v41, 0x45800000, v40
	v_cndmask_b32_e32 v40, v40, v41, vcc
	v_mul_f32_e32 v64, v161, v40

.LBB0_512:
	s_or_b64 exec, exec, s[8:9]
	v_pk_fma_f32 v[50:51], v[6:7], v[50:51], 0 op_sel_hi:[1,1,0]
	v_lshlrev_b32_e32 v78, 16, v138
	v_pk_fma_f32 v[50:51], v[10:11], v[60:61], v[50:51]
	v_and_b32_e32 v79, 0xffff0000, v138
	v_pk_fma_f32 v[50:51], v[98:99], v[80:81], v[50:51]
	v_pk_fma_f32 v[46:47], v[8:9], v[46:47], 0 op_sel_hi:[1,1,0]
	v_pk_fma_f32 v[50:51], v[106:107], v[78:79], v[50:51]
	v_pk_fma_f32 v[46:47], v[12:13], v[58:59], v[46:47]
	v_mul_f32_e32 v52, 0xbfb8aa3b, v50
	v_exp_f32_e32 v52, v52
	v_mul_f32_e32 v53, 0xbfb8aa3b, v51
	v_exp_f32_e32 v53, v53
	v_lshlrev_b32_e32 v64, 16, v139
	v_add_f32_e32 v52, 1.0, v52
	v_rcp_f32_e32 v68, v52
	v_add_f32_e32 v52, 1.0, v53
	v_rcp_f32_e32 v69, v52
	v_and_b32_e32 v65, 0xffff0000, v139
	v_pk_fma_f32 v[46:47], v[100:101], v[66:67], v[46:47]
	v_pk_fma_f32 v[48:49], v[2:3], v[48:49], 0 op_sel_hi:[1,1,0]
	v_pk_fma_f32 v[46:47], v[108:109], v[64:65], v[46:47]
	v_pk_mul_f32 v[50:51], v[50:51], v[68:69]
	v_mul_f32_e32 v68, 0xbfb8aa3b, v46
	v_mul_f32_e32 v69, 0xbfb8aa3b, v47
	v_exp_f32_e32 v68, v68
	v_exp_f32_e32 v69, v69
	v_pk_fma_f32 v[48:49], v[14:15], v[62:63], v[48:49]
	v_lshlrev_b32_e32 v70, 16, v140
	v_and_b32_e32 v71, 0xffff0000, v140
	v_pk_fma_f32 v[48:49], v[102:103], v[72:73], v[48:49]
	v_add_f32_e32 v68, 1.0, v68
	v_pk_fma_f32 v[48:49], v[110:111], v[70:71], v[48:49]
	v_add_f32_e32 v69, 1.0, v69
	v_mul_f32_e32 v76, 0xbfb8aa3b, v48
	v_mul_f32_e32 v77, 0xbfb8aa3b, v49
	v_rcp_f32_e32 v68, v68
	v_rcp_f32_e32 v69, v69
	v_exp_f32_e32 v76, v76
	v_exp_f32_e32 v77, v77
	v_pk_fma_f32 v[44:45], v[4:5], v[44:45], 0 op_sel_hi:[1,1,0]
	v_lshlrev_b32_e32 v52, 16, v141
	v_pk_fma_f32 v[44:45], v[16:17], v[56:57], v[44:45]
	v_and_b32_e32 v53, 0xffff0000, v141
	v_pk_fma_f32 v[44:45], v[104:105], v[54:55], v[44:45]
	v_pk_mul_f32 v[46:47], v[46:47], v[68:69]
	v_add_f32_e32 v68, 1.0, v76
	v_add_f32_e32 v69, 1.0, v77
	v_pk_fma_f32 v[76:77], v[112:113], v[52:53], v[44:45]
	v_rcp_f32_e32 v68, v68
	v_mul_f32_e32 v44, 0xbfb8aa3b, v76
	v_exp_f32_e32 v44, v44
	v_mul_f32_e32 v45, 0xbfb8aa3b, v77
	v_exp_f32_e32 v45, v45
	v_rcp_f32_e32 v69, v69
	v_add_f32_e32 v44, 1.0, v44
	v_rcp_f32_e32 v82, v44
	v_add_f32_e32 v44, 1.0, v45
	v_pk_mul_f32 v[74:75], v[50:51], v[50:51]
	v_rcp_f32_e32 v83, v44
	v_pk_mul_f32 v[84:85], v[46:47], v[46:47]
	v_add_f32_e32 v74, v74, v75
	v_pk_mul_f32 v[44:45], v[48:49], v[68:69]
	v_add_f32_e32 v74, v84, v74
	v_pk_mul_f32 v[48:49], v[44:45], v[44:45]
	v_add_f32_e32 v74, v85, v74
	v_pk_mul_f32 v[68:69], v[76:77], v[82:83]
	v_add_f32_e32 v48, v48, v74
	v_pk_mul_f32 v[76:77], v[68:69], v[68:69]
	v_add_f32_e32 v48, v49, v48
	v_add_f32_e32 v48, v76, v48
	v_add_f32_e32 v48, v77, v48
	v_mov_b32_e32 v74, 1.0
	s_nop 1
	v_add_f32_dpp v48, v48, v48 quad_perm:[1,0,3,2] row_mask:0xf bank_mask:0xf
	s_nop 1
	v_add_f32_dpp v48, v48, v48 quad_perm:[2,3,0,1] row_mask:0xf bank_mask:0xf
	s_nop 1
	v_add_f32_dpp v48, v48, v48 row_half_mirror row_mask:0xf bank_mask:0xf
	s_nop 1
	v_add_f32_dpp v48, v48, v48 row_mirror row_mask:0xf bank_mask:0xf
	s_and_saveexec_b64 s[8:9], s[4:5]
	s_cbranch_execz .LBB0_514
	v_add_f32_e32 v48, 0x358637bd, v48
	v_mul_f32_e32 v49, 0x4b800000, v48
	v_cmp_gt_f32_e32 vcc, s48, v48
	s_nop 1
	v_cndmask_b32_e32 v48, v48, v49, vcc
	v_rsq_f32_e32 v48, v48
	s_nop 0
	v_mul_f32_e32 v49, 0x45800000, v48
	v_cndmask_b32_e32 v48, v48, v49, vcc
	v_mul_f32_e32 v74, v161, v48

.LBB0_516:
	s_or_b64 exec, exec, s[8:9]
	v_pk_fma_f32 v[60:61], v[6:7], v[60:61], 0 op_sel_hi:[1,1,0]
	v_lshlrev_b32_e32 v82, 16, v142
	v_pk_fma_f32 v[60:61], v[10:11], v[80:81], v[60:61]
	v_and_b32_e32 v83, 0xffff0000, v142
	v_pk_fma_f32 v[60:61], v[98:99], v[78:79], v[60:61]
	v_pk_fma_f32 v[58:59], v[8:9], v[58:59], 0 op_sel_hi:[1,1,0]
	v_pk_fma_f32 v[68:69], v[106:107], v[82:83], v[60:61]
	v_pk_fma_f32 v[58:59], v[12:13], v[66:67], v[58:59]
	v_mul_f32_e32 v60, 0xbfb8aa3b, v68
	v_exp_f32_e32 v60, v60
	v_mul_f32_e32 v61, 0xbfb8aa3b, v69
	v_exp_f32_e32 v61, v61
	v_lshlrev_b32_e32 v76, 16, v143
	v_add_f32_e32 v60, 1.0, v60
	v_rcp_f32_e32 v84, v60
	v_add_f32_e32 v60, 1.0, v61
	v_rcp_f32_e32 v85, v60
	v_and_b32_e32 v77, 0xffff0000, v143
	v_pk_fma_f32 v[58:59], v[100:101], v[64:65], v[58:59]
	v_pk_fma_f32 v[62:63], v[2:3], v[62:63], 0 op_sel_hi:[1,1,0]
	v_pk_fma_f32 v[58:59], v[108:109], v[76:77], v[58:59]
	v_pk_mul_f32 v[68:69], v[68:69], v[84:85]
	v_mul_f32_e32 v84, 0xbfb8aa3b, v58
	v_mul_f32_e32 v85, 0xbfb8aa3b, v59
	v_exp_f32_e32 v84, v84
	v_exp_f32_e32 v85, v85
	v_pk_fma_f32 v[62:63], v[14:15], v[72:73], v[62:63]
	v_lshlrev_b32_e32 v74, 16, v144
	v_and_b32_e32 v75, 0xffff0000, v144
	v_pk_fma_f32 v[62:63], v[102:103], v[70:71], v[62:63]
	v_add_f32_e32 v84, 1.0, v84
	v_pk_fma_f32 v[62:63], v[110:111], v[74:75], v[62:63]
	v_add_f32_e32 v85, 1.0, v85
	v_mul_f32_e32 v88, 0xbfb8aa3b, v62
	v_mul_f32_e32 v89, 0xbfb8aa3b, v63
	v_rcp_f32_e32 v84, v84
	v_rcp_f32_e32 v85, v85
	v_exp_f32_e32 v88, v88
	v_exp_f32_e32 v89, v89
	v_pk_fma_f32 v[56:57], v[4:5], v[56:57], 0 op_sel_hi:[1,1,0]
	v_lshlrev_b32_e32 v60, 16, v145
	v_pk_fma_f32 v[56:57], v[16:17], v[54:55], v[56:57]
	v_and_b32_e32 v61, 0xffff0000, v145
	v_pk_fma_f32 v[56:57], v[104:105], v[52:53], v[56:57]
	v_pk_mul_f32 v[58:59], v[58:59], v[84:85]
	v_add_f32_e32 v84, 1.0, v88
	v_add_f32_e32 v85, 1.0, v89
	v_pk_fma_f32 v[88:89], v[112:113], v[60:61], v[56:57]
	v_rcp_f32_e32 v84, v84
	v_mul_f32_e32 v56, 0xbfb8aa3b, v88
	v_exp_f32_e32 v56, v56
	v_mul_f32_e32 v57, 0xbfb8aa3b, v89
	v_exp_f32_e32 v57, v57
	v_rcp_f32_e32 v85, v85
	v_add_f32_e32 v56, 1.0, v56
	v_rcp_f32_e32 v90, v56
	v_add_f32_e32 v56, 1.0, v57
	v_pk_mul_f32 v[86:87], v[68:69], v[68:69]
	v_rcp_f32_e32 v91, v56
	v_pk_mul_f32 v[92:93], v[58:59], v[58:59]
	v_add_f32_e32 v86, v86, v87
	v_pk_mul_f32 v[56:57], v[62:63], v[84:85]
	v_add_f32_e32 v86, v92, v86
	v_pk_mul_f32 v[62:63], v[56:57], v[56:57]
	v_add_f32_e32 v86, v93, v86
	v_pk_mul_f32 v[84:85], v[88:89], v[90:91]
	v_add_f32_e32 v62, v62, v86
	v_pk_mul_f32 v[88:89], v[84:85], v[84:85]
	v_add_f32_e32 v62, v63, v62
	v_add_f32_e32 v62, v88, v62
	v_add_f32_e32 v62, v89, v62
	v_mov_b32_e32 v86, 1.0
	s_nop 1
	v_add_f32_dpp v62, v62, v62 quad_perm:[1,0,3,2] row_mask:0xf bank_mask:0xf
	s_nop 1
	v_add_f32_dpp v62, v62, v62 quad_perm:[2,3,0,1] row_mask:0xf bank_mask:0xf
	s_nop 1
	v_add_f32_dpp v62, v62, v62 row_half_mirror row_mask:0xf bank_mask:0xf
	s_nop 1
	v_add_f32_dpp v62, v62, v62 row_mirror row_mask:0xf bank_mask:0xf
	s_and_saveexec_b64 s[8:9], s[4:5]
	s_cbranch_execz .LBB0_518
	v_add_f32_e32 v62, 0x358637bd, v62
	v_mul_f32_e32 v63, 0x4b800000, v62
	v_cmp_gt_f32_e32 vcc, s48, v62
	s_nop 1
	v_cndmask_b32_e32 v62, v62, v63, vcc
	v_rsq_f32_e32 v62, v62
	s_nop 0
	v_mul_f32_e32 v63, 0x45800000, v62
	v_cndmask_b32_e32 v62, v62, v63, vcc
	v_mul_f32_e32 v86, v161, v62

.LBB0_520:
	s_or_b64 exec, exec, s[8:9]
	v_pk_fma_f32 v[80:81], v[6:7], v[80:81], 0 op_sel_hi:[1,1,0]
	v_lshlrev_b32_e32 v90, 16, v146
	v_pk_fma_f32 v[80:81], v[10:11], v[78:79], v[80:81]
	v_and_b32_e32 v91, 0xffff0000, v146
	v_pk_fma_f32 v[80:81], v[98:99], v[82:83], v[80:81]
	v_pk_fma_f32 v[66:67], v[8:9], v[66:67], 0 op_sel_hi:[1,1,0]
	v_pk_fma_f32 v[84:85], v[106:107], v[90:91], v[80:81]
	v_pk_fma_f32 v[66:67], v[12:13], v[64:65], v[66:67]
	v_mul_f32_e32 v80, 0xbfb8aa3b, v84
	v_exp_f32_e32 v80, v80
	v_mul_f32_e32 v81, 0xbfb8aa3b, v85
	v_exp_f32_e32 v81, v81
	v_lshlrev_b32_e32 v88, 16, v147
	v_add_f32_e32 v80, 1.0, v80
	v_rcp_f32_e32 v92, v80
	v_add_f32_e32 v80, 1.0, v81
	v_rcp_f32_e32 v93, v80
	v_and_b32_e32 v89, 0xffff0000, v147
	v_pk_fma_f32 v[66:67], v[100:101], v[76:77], v[66:67]
	v_pk_fma_f32 v[72:73], v[2:3], v[72:73], 0 op_sel_hi:[1,1,0]
	v_pk_fma_f32 v[66:67], v[108:109], v[88:89], v[66:67]
	v_pk_mul_f32 v[84:85], v[84:85], v[92:93]
	v_mul_f32_e32 v92, 0xbfb8aa3b, v66
	v_mul_f32_e32 v93, 0xbfb8aa3b, v67
	v_exp_f32_e32 v92, v92
	v_exp_f32_e32 v93, v93
	v_pk_fma_f32 v[72:73], v[14:15], v[70:71], v[72:73]
	v_lshlrev_b32_e32 v86, 16, v148
	v_and_b32_e32 v87, 0xffff0000, v148
	v_pk_fma_f32 v[72:73], v[102:103], v[74:75], v[72:73]
	v_add_f32_e32 v92, 1.0, v92
	v_pk_fma_f32 v[72:73], v[110:111], v[86:87], v[72:73]
	v_add_f32_e32 v93, 1.0, v93
	v_mul_f32_e32 v96, 0xbfb8aa3b, v72
	v_mul_f32_e32 v97, 0xbfb8aa3b, v73
	v_rcp_f32_e32 v92, v92
	v_rcp_f32_e32 v93, v93
	v_exp_f32_e32 v96, v96
	v_exp_f32_e32 v97, v97
	v_pk_fma_f32 v[54:55], v[4:5], v[54:55], 0 op_sel_hi:[1,1,0]
	v_lshlrev_b32_e32 v80, 16, v149
	v_pk_fma_f32 v[54:55], v[16:17], v[52:53], v[54:55]
	v_and_b32_e32 v81, 0xffff0000, v149
	v_pk_fma_f32 v[54:55], v[104:105], v[60:61], v[54:55]
	v_pk_mul_f32 v[66:67], v[66:67], v[92:93]
	v_add_f32_e32 v92, 1.0, v96
	v_add_f32_e32 v93, 1.0, v97
	v_pk_fma_f32 v[96:97], v[112:113], v[80:81], v[54:55]
	v_rcp_f32_e32 v92, v92
	v_mul_f32_e32 v54, 0xbfb8aa3b, v96
	v_exp_f32_e32 v54, v54
	v_mul_f32_e32 v55, 0xbfb8aa3b, v97
	v_exp_f32_e32 v55, v55
	v_rcp_f32_e32 v93, v93
	v_add_f32_e32 v54, 1.0, v54
	v_rcp_f32_e32 v162, v54
	v_add_f32_e32 v54, 1.0, v55
	v_pk_mul_f32 v[94:95], v[84:85], v[84:85]
	v_rcp_f32_e32 v163, v54
	v_pk_mul_f32 v[164:165], v[66:67], v[66:67]
	v_add_f32_e32 v94, v94, v95
	v_pk_mul_f32 v[54:55], v[72:73], v[92:93]
	v_add_f32_e32 v94, v164, v94
	v_pk_mul_f32 v[72:73], v[54:55], v[54:55]
	v_add_f32_e32 v94, v165, v94
	v_pk_mul_f32 v[92:93], v[96:97], v[162:163]
	v_add_f32_e32 v72, v72, v94
	v_pk_mul_f32 v[96:97], v[92:93], v[92:93]
	v_add_f32_e32 v72, v73, v72
	v_add_f32_e32 v72, v96, v72
	v_add_f32_e32 v72, v97, v72
	v_mov_b32_e32 v94, 1.0
	s_nop 1
	v_add_f32_dpp v72, v72, v72 quad_perm:[1,0,3,2] row_mask:0xf bank_mask:0xf
	s_nop 1
	v_add_f32_dpp v72, v72, v72 quad_perm:[2,3,0,1] row_mask:0xf bank_mask:0xf
	s_nop 1
	v_add_f32_dpp v72, v72, v72 row_half_mirror row_mask:0xf bank_mask:0xf
	s_nop 1
	v_add_f32_dpp v72, v72, v72 row_mirror row_mask:0xf bank_mask:0xf
	s_and_saveexec_b64 s[8:9], s[4:5]
	s_cbranch_execz .LBB0_522
	v_add_f32_e32 v72, 0x358637bd, v72
	v_mul_f32_e32 v73, 0x4b800000, v72
	v_cmp_gt_f32_e32 vcc, s48, v72
	s_nop 1
	v_cndmask_b32_e32 v72, v72, v73, vcc
	v_rsq_f32_e32 v72, v72
	s_nop 0
	v_mul_f32_e32 v73, 0x45800000, v72
	v_cndmask_b32_e32 v72, v72, v73, vcc
	v_mul_f32_e32 v94, v161, v72

.LBB0_524:
	s_or_b64 exec, exec, s[8:9]
	v_pk_fma_f32 v[78:79], v[6:7], v[78:79], 0 op_sel_hi:[1,1,0]
	v_lshlrev_b32_e32 v162, 16, v150
	v_pk_fma_f32 v[78:79], v[10:11], v[82:83], v[78:79]
	v_and_b32_e32 v163, 0xffff0000, v150
	v_pk_fma_f32 v[78:79], v[98:99], v[90:91], v[78:79]
	v_pk_fma_f32 v[64:65], v[8:9], v[64:65], 0 op_sel_hi:[1,1,0]
	v_pk_fma_f32 v[78:79], v[106:107], v[162:163], v[78:79]
	v_pk_fma_f32 v[64:65], v[12:13], v[76:77], v[64:65]
	v_mul_f32_e32 v92, 0xbfb8aa3b, v78
	v_exp_f32_e32 v92, v92
	v_mul_f32_e32 v93, 0xbfb8aa3b, v79
	v_exp_f32_e32 v93, v93
	v_lshlrev_b32_e32 v96, 16, v151
	v_add_f32_e32 v92, 1.0, v92
	v_rcp_f32_e32 v164, v92
	v_add_f32_e32 v92, 1.0, v93
	v_rcp_f32_e32 v165, v92
	v_and_b32_e32 v97, 0xffff0000, v151
	v_pk_fma_f32 v[64:65], v[100:101], v[88:89], v[64:65]
	v_pk_fma_f32 v[70:71], v[2:3], v[70:71], 0 op_sel_hi:[1,1,0]
	v_pk_fma_f32 v[64:65], v[108:109], v[96:97], v[64:65]
	v_pk_mul_f32 v[78:79], v[78:79], v[164:165]
	v_mul_f32_e32 v164, 0xbfb8aa3b, v64
	v_mul_f32_e32 v165, 0xbfb8aa3b, v65
	v_exp_f32_e32 v164, v164
	v_exp_f32_e32 v165, v165
	v_pk_fma_f32 v[70:71], v[14:15], v[74:75], v[70:71]
	v_lshlrev_b32_e32 v94, 16, v152
	v_and_b32_e32 v95, 0xffff0000, v152
	v_pk_fma_f32 v[70:71], v[102:103], v[86:87], v[70:71]
	v_add_f32_e32 v164, 1.0, v164
	v_pk_fma_f32 v[70:71], v[110:111], v[94:95], v[70:71]
	v_add_f32_e32 v165, 1.0, v165
	v_mul_f32_e32 v166, 0xbfb8aa3b, v70
	v_rcp_f32_e32 v164, v164
	v_rcp_f32_e32 v165, v165
	v_exp_f32_e32 v166, v166
	v_mul_f32_e32 v178, 0xbfb8aa3b, v71
	v_pk_fma_f32 v[52:53], v[4:5], v[52:53], 0 op_sel_hi:[1,1,0]
	v_exp_f32_e32 v178, v178
	v_pk_fma_f32 v[52:53], v[16:17], v[60:61], v[52:53]
	v_lshlrev_b32_e32 v92, 16, v153
	v_and_b32_e32 v93, 0xffff0000, v153
	v_pk_fma_f32 v[52:53], v[104:105], v[80:81], v[52:53]
	v_pk_mul_f32 v[64:65], v[64:65], v[164:165]
	v_pk_fma_f32 v[52:53], v[112:113], v[92:93], v[52:53]
	v_add_f32_e32 v164, 1.0, v166
	v_mul_f32_e32 v166, 0xbfb8aa3b, v52
	v_add_f32_e32 v165, 1.0, v178
	v_exp_f32_e32 v166, v166
	v_mul_f32_e32 v178, 0xbfb8aa3b, v53
	v_exp_f32_e32 v179, v178
	v_rcp_f32_e32 v164, v164
	v_rcp_f32_e32 v165, v165
	v_add_f32_e32 v166, 1.0, v166
	v_rcp_f32_e32 v178, v166
	v_add_f32_e32 v166, 1.0, v179
	v_pk_mul_f32 v[176:177], v[78:79], v[78:79]
	v_rcp_f32_e32 v179, v166
	v_pk_mul_f32 v[180:181], v[64:65], v[64:65]
	v_add_f32_e32 v166, v176, v177
	v_pk_mul_f32 v[70:71], v[70:71], v[164:165]
	v_add_f32_e32 v166, v180, v166
	v_pk_mul_f32 v[182:183], v[70:71], v[70:71]
	v_add_f32_e32 v166, v181, v166
	v_pk_mul_f32 v[164:165], v[52:53], v[178:179]
	v_add_f32_e32 v166, v182, v166
	v_pk_mul_f32 v[52:53], v[164:165], v[164:165]
	v_add_f32_e32 v166, v183, v166
	v_add_f32_e32 v52, v52, v166
	v_add_f32_e32 v52, v53, v52
	v_mov_b32_e32 v166, 1.0
	s_nop 1
	v_add_f32_dpp v52, v52, v52 quad_perm:[1,0,3,2] row_mask:0xf bank_mask:0xf
	s_nop 1
	v_add_f32_dpp v52, v52, v52 quad_perm:[2,3,0,1] row_mask:0xf bank_mask:0xf
	s_nop 1
	v_add_f32_dpp v52, v52, v52 row_half_mirror row_mask:0xf bank_mask:0xf
	s_nop 1
	v_add_f32_dpp v52, v52, v52 row_mirror row_mask:0xf bank_mask:0xf
	s_and_saveexec_b64 s[8:9], s[4:5]
	s_cbranch_execz .LBB0_526
	v_add_f32_e32 v52, 0x358637bd, v52
	v_mul_f32_e32 v53, 0x4b800000, v52
	v_cmp_gt_f32_e32 vcc, s48, v52
	s_nop 1
	v_cndmask_b32_e32 v52, v52, v53, vcc
	v_rsq_f32_e32 v52, v52
	s_nop 0
	v_mul_f32_e32 v53, 0x45800000, v52
	v_cndmask_b32_e32 v52, v52, v53, vcc
	v_mul_f32_e32 v166, v161, v52

.LBB0_528:
	s_or_b64 exec, exec, s[8:9]
	v_pk_fma_f32 v[82:83], v[6:7], v[82:83], 0 op_sel_hi:[1,1,0]
	v_pk_fma_f32 v[76:77], v[8:9], v[76:77], 0 op_sel_hi:[1,1,0]
	v_pk_fma_f32 v[82:83], v[10:11], v[90:91], v[82:83]
	v_lshlrev_b32_e32 v90, 16, v154
	v_pk_fma_f32 v[82:83], v[98:99], v[162:163], v[82:83]
	v_and_b32_e32 v91, 0xffff0000, v154
	v_pk_fma_f32 v[82:83], v[106:107], v[90:91], v[82:83]
	v_pk_fma_f32 v[76:77], v[12:13], v[88:89], v[76:77]
	v_mul_f32_e32 v90, 0xbfb8aa3b, v82
	v_mul_f32_e32 v91, 0xbfb8aa3b, v83
	v_exp_f32_e32 v90, v90
	v_exp_f32_e32 v91, v91
	v_pk_fma_f32 v[76:77], v[100:101], v[96:97], v[76:77]
	v_lshlrev_b32_e32 v88, 16, v155
	v_add_f32_e32 v90, 1.0, v90
	v_add_f32_e32 v91, 1.0, v91
	v_rcp_f32_e32 v90, v90
	v_rcp_f32_e32 v91, v91
	v_and_b32_e32 v89, 0xffff0000, v155
	v_pk_fma_f32 v[76:77], v[108:109], v[88:89], v[76:77]
	v_pk_fma_f32 v[74:75], v[2:3], v[74:75], 0 op_sel_hi:[1,1,0]
	v_mul_f32_e32 v88, 0xbfb8aa3b, v76
	v_pk_mul_f32 v[82:83], v[82:83], v[90:91]
	v_exp_f32_e32 v90, v88
	v_mul_f32_e32 v88, 0xbfb8aa3b, v77
	v_exp_f32_e32 v91, v88
	v_pk_fma_f32 v[74:75], v[14:15], v[86:87], v[74:75]
	v_lshlrev_b32_e32 v86, 16, v156
	v_pk_fma_f32 v[74:75], v[102:103], v[94:95], v[74:75]
	v_and_b32_e32 v87, 0xffff0000, v156
	v_pk_fma_f32 v[86:87], v[110:111], v[86:87], v[74:75]
	v_pk_fma_f32 v[60:61], v[4:5], v[60:61], 0 op_sel_hi:[1,1,0]
	v_mul_f32_e32 v74, 0xbfb8aa3b, v86
	v_pk_fma_f32 v[60:61], v[16:17], v[80:81], v[60:61]
	v_add_f32_e32 v90, 1.0, v90
	v_add_f32_e32 v91, 1.0, v91
	v_exp_f32_e32 v94, v74
	v_mul_f32_e32 v74, 0xbfb8aa3b, v87
	v_pk_fma_f32 v[60:61], v[104:105], v[92:93], v[60:61]
	v_lshlrev_b32_e32 v80, 16, v157
	v_and_b32_e32 v81, 0xffff0000, v157
	v_rcp_f32_e32 v90, v90
	v_rcp_f32_e32 v91, v91
	v_exp_f32_e32 v95, v74
	v_pk_fma_f32 v[60:61], v[112:113], v[80:81], v[60:61]
	v_pk_mul_f32 v[88:89], v[82:83], v[82:83]
	v_mul_f32_e32 v80, 0xbfb8aa3b, v60
	v_mul_f32_e32 v81, 0xbfb8aa3b, v61
	v_exp_f32_e32 v80, v80
	v_exp_f32_e32 v81, v81
	v_pk_mul_f32 v[74:75], v[76:77], v[90:91]
	v_add_f32_e32 v76, 1.0, v94
	v_add_f32_e32 v77, 1.0, v95
	v_rcp_f32_e32 v76, v76
	v_rcp_f32_e32 v77, v77
	v_add_f32_e32 v80, 1.0, v80
	v_add_f32_e32 v81, 1.0, v81
	v_rcp_f32_e32 v80, v80
	v_rcp_f32_e32 v81, v81
	v_pk_mul_f32 v[90:91], v[74:75], v[74:75]
	v_add_f32_e32 v88, v88, v89
	v_pk_mul_f32 v[76:77], v[86:87], v[76:77]
	v_add_f32_e32 v88, v90, v88
	v_pk_mul_f32 v[86:87], v[76:77], v[76:77]
	v_add_f32_e32 v88, v91, v88
	v_pk_mul_f32 v[80:81], v[60:61], v[80:81]
	v_add_f32_e32 v86, v86, v88
	v_pk_mul_f32 v[60:61], v[80:81], v[80:81]
	v_add_f32_e32 v86, v87, v86
	v_add_f32_e32 v60, v60, v86
	v_add_f32_e32 v60, v61, v60
	v_mov_b32_e32 v86, 1.0
	s_nop 1
	v_add_f32_dpp v19, v60, v60 quad_perm:[1,0,3,2] row_mask:0xf bank_mask:0xf
	s_nop 1
	v_add_f32_dpp v19, v19, v19 quad_perm:[2,3,0,1] row_mask:0xf bank_mask:0xf
	s_nop 1
	v_add_f32_dpp v19, v19, v19 row_half_mirror row_mask:0xf bank_mask:0xf
	s_nop 1
	v_add_f32_dpp v19, v19, v19 row_mirror row_mask:0xf bank_mask:0xf
	s_and_saveexec_b64 s[8:9], s[4:5]
	s_cbranch_execz .LBB0_530
	v_add_f32_e32 v19, 0x358637bd, v19
	v_mul_f32_e32 v60, 0x4b800000, v19
	v_cmp_gt_f32_e32 vcc, s48, v19
	s_nop 1
	v_cndmask_b32_e32 v19, v19, v60, vcc
	v_rsq_f32_e32 v19, v19
	s_nop 0
	v_mul_f32_e32 v60, 0x45800000, v19
	v_cndmask_b32_e32 v19, v19, v60, vcc
	v_mul_f32_e32 v86, v161, v19
